# attention loop: last trip peeled, no LDS-DMA issued for key tiles past the end (the tail no longer waits for them)
# speedup vs baseline: 1.0019x; 1.0019x over previous
.Latt_bs_3:
	v_add_f32_e32 v225, v225, v209
	v_add_f32_e32 v166, v166, v210
	v_add_f32_e32 v175, v175, v211
	v_add_f32_e32 v202, v202, v212
	s_add_i32 m0, s17, 65536
	ds_read_b128 v[112:115], v178
	global_load_lds_dwordx4 v181, s[36:37]
	s_waitcnt lgkmcnt(5)
	v_mfma_f32_32x32x16_bf16 v[48:63], v[230:233], v[152:155], v[48:63]
	v_add_f32_e32 v225, v225, v213
	v_add_f32_e32 v166, v166, v214
	v_add_f32_e32 v175, v175, v215
	v_add_f32_e32 v202, v202, v216
	s_add_i32 m0, s17, 66560
	ds_read_b128 v[116:119], v128
	global_load_lds_dwordx4 v165, s[36:37]
	s_waitcnt lgkmcnt(4)
	v_mfma_f32_32x32x16_bf16 v[32:47], v[234:237], v[152:155], v[32:47]
	v_add_f32_e32 v225, v225, v217
	v_add_f32_e32 v166, v166, v218
	v_add_f32_e32 v175, v175, v219
	v_add_f32_e32 v202, v202, v220
	s_add_i32 m0, s17, 81920
	ds_read_b128 v[120:123], v130
	global_load_lds_dwordx4 v207, s[36:37]
	s_waitcnt lgkmcnt(3)
	v_mfma_f32_32x32x16_bf16 v[16:31], v[238:241], v[152:155], v[16:31]
	v_add_f32_e32 v225, v225, v221
	v_add_f32_e32 v166, v166, v222
	v_add_f32_e32 v175, v175, v223
	v_add_f32_e32 v202, v202, v224
	s_add_i32 m0, s17, 82944
	ds_read_b128 v[124:127], v131
	global_load_lds_dwordx4 v208, s[36:37]
	s_add_u32 s36, s36, 0x68000
	s_addc_u32 s37, s37, 0
	s_cmp_eq_u32 s16, 0
	s_cselect_b32 s36, s38, s36
	s_cselect_b32 s37, s39, s37
	s_add_i32 s16, s16, 1
	s_cmpk_lt_u32 s16, 0x80
	s_cbranch_scc1 .Latt_loop
	s_waitcnt lgkmcnt(3)
	v_mfma_f32_32x32x16_bf16 v[96:111], v[112:115], v[140:143], v[0:15]
	v_exp_f32_e32 v209, v80
	v_exp_f32_e32 v210, v81
	ds_read_b64_tr_b16 v[226:227], v198 offset:40960
	ds_read_b64_tr_b16 v[228:229], v198 offset:43008
	s_waitcnt lgkmcnt(4)
	v_mfma_f32_32x32x16_bf16 v[96:111], v[116:119], v[144:147], v[96:111]
	v_exp_f32_e32 v211, v82
	v_exp_f32_e32 v212, v83
	v_cvt_pk_bf16_f32 v156, v209, v210
	ds_read_b64_tr_b16 v[230:231], v199 offset:40960
	ds_read_b64_tr_b16 v[232:233], v199 offset:43008
	s_waitcnt lgkmcnt(5)
	v_mfma_f32_32x32x16_bf16 v[96:111], v[120:123], v[136:139], v[96:111]
	v_exp_f32_e32 v213, v84
	v_exp_f32_e32 v214, v85
	v_cvt_pk_bf16_f32 v157, v211, v212
	ds_read_b64_tr_b16 v[234:235], v201 offset:40960
	ds_read_b64_tr_b16 v[236:237], v201 offset:43008
	s_waitcnt lgkmcnt(6)
	v_mfma_f32_32x32x16_bf16 v[96:111], v[124:127], v[132:135], v[96:111]
	v_exp_f32_e32 v215, v86
	v_exp_f32_e32 v216, v87
	v_cvt_pk_bf16_f32 v158, v213, v214
	v_cvt_pk_bf16_f32 v159, v215, v216
	ds_read_b64_tr_b16 v[238:239], v203 offset:40960
	ds_read_b64_tr_b16 v[240:241], v203 offset:43008
	s_waitcnt lgkmcnt(6)
	v_mfma_f32_32x32x16_bf16 v[64:79], v[226:229], v[156:159], v[64:79]
	v_exp_f32_e32 v217, v88
	v_exp_f32_e32 v218, v89
	ds_read_b64_tr_b16 v[242:243], v198 offset:45056
	ds_read_b64_tr_b16 v[244:245], v198 offset:47104
	s_waitcnt lgkmcnt(6)
	v_mfma_f32_32x32x16_bf16 v[48:63], v[230:233], v[156:159], v[48:63]
	v_exp_f32_e32 v219, v90
	v_exp_f32_e32 v220, v91
	v_cvt_pk_bf16_f32 v160, v217, v218
	ds_read_b64_tr_b16 v[246:247], v199 offset:45056
	ds_read_b64_tr_b16 v[248:249], v199 offset:47104
	s_waitcnt lgkmcnt(6)
	v_mfma_f32_32x32x16_bf16 v[32:47], v[234:237], v[156:159], v[32:47]
	v_exp_f32_e32 v221, v92
	v_exp_f32_e32 v222, v93
	v_cvt_pk_bf16_f32 v161, v219, v220
	ds_read_b64_tr_b16 v[226:227], v201 offset:45056
	ds_read_b64_tr_b16 v[228:229], v201 offset:47104
	s_waitcnt lgkmcnt(6)
	v_mfma_f32_32x32x16_bf16 v[16:31], v[238:241], v[156:159], v[16:31]
	v_exp_f32_e32 v223, v94
	v_exp_f32_e32 v224, v95
	v_cvt_pk_bf16_f32 v162, v221, v222
	v_cvt_pk_bf16_f32 v163, v223, v224
	ds_read_b64_tr_b16 v[230:231], v203 offset:45056
	ds_read_b64_tr_b16 v[232:233], v203 offset:47104
	s_waitcnt lgkmcnt(6)
	v_mfma_f32_32x32x16_bf16 v[64:79], v[242:245], v[160:163], v[64:79]
	v_add_f32_e32 v225, v225, v209
	v_add_f32_e32 v166, v166, v210
	v_add_f32_e32 v175, v175, v211
	v_add_f32_e32 v202, v202, v212
	ds_read_b128 v[112:115], v178 offset:8192
	s_waitcnt lgkmcnt(5)
	v_mfma_f32_32x32x16_bf16 v[48:63], v[246:249], v[160:163], v[48:63]
	v_add_f32_e32 v225, v225, v213
	v_add_f32_e32 v166, v166, v214
	v_add_f32_e32 v175, v175, v215
	v_add_f32_e32 v202, v202, v216
	ds_read_b128 v[116:119], v128 offset:8192
	s_waitcnt lgkmcnt(4)
	v_mfma_f32_32x32x16_bf16 v[32:47], v[226:229], v[160:163], v[32:47]
	v_add_f32_e32 v225, v225, v217
	v_add_f32_e32 v166, v166, v218
	v_add_f32_e32 v175, v175, v219
	v_add_f32_e32 v202, v202, v220
	ds_read_b128 v[120:123], v130 offset:8192
	s_waitcnt lgkmcnt(3)
	v_mfma_f32_32x32x16_bf16 v[16:31], v[230:233], v[160:163], v[16:31]
	v_add_f32_e32 v225, v225, v221
	v_add_f32_e32 v166, v166, v222
	v_add_f32_e32 v175, v175, v223
	v_add_f32_e32 v202, v202, v224
	ds_read_b128 v[124:127], v131 offset:8192
	s_waitcnt lgkmcnt(3)
	v_mfma_f32_32x32x16_bf16 v[80:95], v[112:115], v[140:143], v[0:15]
	v_exp_f32_e32 v209, v96
	v_exp_f32_e32 v210, v97
	ds_read_b64_tr_b16 v[234:235], v184
	ds_read_b64_tr_b16 v[236:237], v184 offset:2048
	s_waitcnt lgkmcnt(4)
	v_mfma_f32_32x32x16_bf16 v[80:95], v[116:119], v[144:147], v[80:95]
	v_exp_f32_e32 v211, v98
	v_exp_f32_e32 v212, v99
	v_cvt_pk_bf16_f32 v148, v209, v210
	ds_read_b64_tr_b16 v[238:239], v185
	ds_read_b64_tr_b16 v[240:241], v185 offset:2048
	s_waitcnt lgkmcnt(5)
	v_mfma_f32_32x32x16_bf16 v[80:95], v[120:123], v[136:139], v[80:95]
	v_exp_f32_e32 v213, v100
	v_exp_f32_e32 v214, v101
	v_cvt_pk_bf16_f32 v149, v211, v212
	ds_read_b64_tr_b16 v[242:243], v186
	ds_read_b64_tr_b16 v[244:245], v186 offset:2048
	s_waitcnt lgkmcnt(6)
	v_mfma_f32_32x32x16_bf16 v[80:95], v[124:127], v[132:135], v[80:95]
	v_exp_f32_e32 v215, v102
	v_exp_f32_e32 v216, v103
	v_cvt_pk_bf16_f32 v150, v213, v214
	v_cvt_pk_bf16_f32 v151, v215, v216
	ds_read_b64_tr_b16 v[246:247], v187
	ds_read_b64_tr_b16 v[248:249], v187 offset:2048
	s_waitcnt lgkmcnt(6)
	v_mfma_f32_32x32x16_bf16 v[64:79], v[234:237], v[148:151], v[64:79]
	v_exp_f32_e32 v217, v104
	v_exp_f32_e32 v218, v105
	ds_read_b64_tr_b16 v[226:227], v184 offset:4096
	ds_read_b64_tr_b16 v[228:229], v184 offset:6144
	s_waitcnt lgkmcnt(6)
	v_mfma_f32_32x32x16_bf16 v[48:63], v[238:241], v[148:151], v[48:63]
	v_exp_f32_e32 v219, v106
	v_exp_f32_e32 v220, v107
	v_cvt_pk_bf16_f32 v152, v217, v218
	ds_read_b64_tr_b16 v[230:231], v185 offset:4096
	ds_read_b64_tr_b16 v[232:233], v185 offset:6144
	s_waitcnt lgkmcnt(6)
	v_mfma_f32_32x32x16_bf16 v[32:47], v[242:245], v[148:151], v[32:47]
	v_exp_f32_e32 v221, v108
	v_exp_f32_e32 v222, v109
	v_cvt_pk_bf16_f32 v153, v219, v220
	ds_read_b64_tr_b16 v[234:235], v186 offset:4096
	ds_read_b64_tr_b16 v[236:237], v186 offset:6144
	s_waitcnt lgkmcnt(6)
	v_mfma_f32_32x32x16_bf16 v[16:31], v[246:249], v[148:151], v[16:31]
	v_exp_f32_e32 v223, v110
	v_exp_f32_e32 v224, v111
	v_cvt_pk_bf16_f32 v154, v221, v222
	v_cvt_pk_bf16_f32 v155, v223, v224
	ds_read_b64_tr_b16 v[238:239], v187 offset:4096
	ds_read_b64_tr_b16 v[240:241], v187 offset:6144
	s_waitcnt lgkmcnt(6)
	v_mfma_f32_32x32x16_bf16 v[64:79], v[226:229], v[152:155], v[64:79]
	s_waitcnt vmcnt(4)
	s_barrier
	s_and_b32 s1, s35, 3
	s_add_i32 s35, s35, 1
	s_cmp_lg_u32 s1, 0
	s_cbranch_scc1 .Latt_bs_0p
	v_lshlrev_b32_e32 v204, 16, v194
	v_and_b32_e32 v205, 0xffff0000, v194
	v_fma_f32 v182, v174, v182, v204
	v_fma_f32 v183, v174, v183, v205
	s_lshr_b32 s1, s35, 2
	s_add_i32 s1, s1, 1
	s_cmpk_lt_u32 s1, 0x84
	s_cbranch_scc0 .Latt_bs_0p
	s_lshl_b32 s2, s1, 14
	s_mov_b32 s3, 0
	s_lshl_b32 s4, s1, 8
	s_mov_b32 s5, 0
	v_lshl_add_u64 v[204:205], v[168:169], 0, s[2:3]
	v_lshl_add_u64 v[196:197], v[170:171], 0, s[4:5]
	v_cvt_pk_bf16_f32 v206, v182, v183
	global_load_dword v194, v[204:205], off
	global_load_dword v174, v[196:197], off
	global_store_dword v[204:205], v206, off

.Latt_bs_1p:
	v_add_f32_e32 v225, v225, v209
	v_add_f32_e32 v166, v166, v210
	v_add_f32_e32 v175, v175, v211
	v_add_f32_e32 v202, v202, v212
	ds_read_b128 v[112:115], v180
	s_waitcnt lgkmcnt(5)
	v_mfma_f32_32x32x16_bf16 v[48:63], v[246:249], v[152:155], v[48:63]
	v_add_f32_e32 v225, v225, v213
	v_add_f32_e32 v166, v166, v214
	v_add_f32_e32 v175, v175, v215
	v_add_f32_e32 v202, v202, v216
	ds_read_b128 v[116:119], v189
	s_waitcnt lgkmcnt(4)
	v_mfma_f32_32x32x16_bf16 v[32:47], v[226:229], v[152:155], v[32:47]
	v_add_f32_e32 v225, v225, v217
	v_add_f32_e32 v166, v166, v218
	v_add_f32_e32 v175, v175, v219
	v_add_f32_e32 v202, v202, v220
	ds_read_b128 v[120:123], v191
	s_waitcnt lgkmcnt(3)
	v_mfma_f32_32x32x16_bf16 v[16:31], v[230:233], v[152:155], v[16:31]
	v_add_f32_e32 v225, v225, v221
	v_add_f32_e32 v166, v166, v222
	v_add_f32_e32 v175, v175, v223
	v_add_f32_e32 v202, v202, v224
	ds_read_b128 v[124:127], v192
	s_add_i32 s16, s16, 1
	s_waitcnt lgkmcnt(3)
	v_mfma_f32_32x32x16_bf16 v[96:111], v[112:115], v[140:143], v[0:15]
	v_exp_f32_e32 v209, v80
	v_exp_f32_e32 v210, v81
	ds_read_b64_tr_b16 v[234:235], v184 offset:40960
	ds_read_b64_tr_b16 v[236:237], v184 offset:43008
	s_waitcnt lgkmcnt(4)
	v_mfma_f32_32x32x16_bf16 v[96:111], v[116:119], v[144:147], v[96:111]
	v_exp_f32_e32 v211, v82
	v_exp_f32_e32 v212, v83
	v_cvt_pk_bf16_f32 v156, v209, v210
	ds_read_b64_tr_b16 v[238:239], v185 offset:40960
	ds_read_b64_tr_b16 v[240:241], v185 offset:43008
	s_waitcnt lgkmcnt(5)
	v_mfma_f32_32x32x16_bf16 v[96:111], v[120:123], v[136:139], v[96:111]
	v_exp_f32_e32 v213, v84
	v_exp_f32_e32 v214, v85
	v_cvt_pk_bf16_f32 v157, v211, v212
	ds_read_b64_tr_b16 v[242:243], v186 offset:40960
	ds_read_b64_tr_b16 v[244:245], v186 offset:43008
	s_waitcnt lgkmcnt(6)
	v_mfma_f32_32x32x16_bf16 v[96:111], v[124:127], v[132:135], v[96:111]
	v_exp_f32_e32 v215, v86
	v_exp_f32_e32 v216, v87
	v_cvt_pk_bf16_f32 v158, v213, v214
	v_cvt_pk_bf16_f32 v159, v215, v216
	ds_read_b64_tr_b16 v[246:247], v187 offset:40960
	ds_read_b64_tr_b16 v[248:249], v187 offset:43008
	s_waitcnt lgkmcnt(6)
	v_mfma_f32_32x32x16_bf16 v[64:79], v[234:237], v[156:159], v[64:79]
	v_exp_f32_e32 v217, v88
	v_exp_f32_e32 v218, v89
	ds_read_b64_tr_b16 v[226:227], v184 offset:45056
	ds_read_b64_tr_b16 v[228:229], v184 offset:47104
	s_waitcnt lgkmcnt(6)
	v_mfma_f32_32x32x16_bf16 v[48:63], v[238:241], v[156:159], v[48:63]
	v_exp_f32_e32 v219, v90
	v_exp_f32_e32 v220, v91
	v_cvt_pk_bf16_f32 v160, v217, v218
	ds_read_b64_tr_b16 v[230:231], v185 offset:45056
	ds_read_b64_tr_b16 v[232:233], v185 offset:47104
	s_waitcnt lgkmcnt(6)
	v_mfma_f32_32x32x16_bf16 v[32:47], v[242:245], v[156:159], v[32:47]
	v_exp_f32_e32 v221, v92
	v_exp_f32_e32 v222, v93
	v_cvt_pk_bf16_f32 v161, v219, v220
	ds_read_b64_tr_b16 v[234:235], v186 offset:45056
	ds_read_b64_tr_b16 v[236:237], v186 offset:47104
	s_waitcnt lgkmcnt(6)
	v_mfma_f32_32x32x16_bf16 v[16:31], v[246:249], v[156:159], v[16:31]
	v_exp_f32_e32 v223, v94
	v_exp_f32_e32 v224, v95
	v_cvt_pk_bf16_f32 v162, v221, v222
	v_cvt_pk_bf16_f32 v163, v223, v224
	ds_read_b64_tr_b16 v[238:239], v187 offset:45056
	ds_read_b64_tr_b16 v[240:241], v187 offset:47104
	s_waitcnt lgkmcnt(6)
	v_mfma_f32_32x32x16_bf16 v[64:79], v[226:229], v[160:163], v[64:79]
	v_add_f32_e32 v225, v225, v209
	v_add_f32_e32 v166, v166, v210
	v_add_f32_e32 v175, v175, v211
	v_add_f32_e32 v202, v202, v212
	ds_read_b128 v[112:115], v180 offset:8192
	s_waitcnt lgkmcnt(5)
	v_mfma_f32_32x32x16_bf16 v[48:63], v[230:233], v[160:163], v[48:63]
	v_add_f32_e32 v225, v225, v213
	v_add_f32_e32 v166, v166, v214
	v_add_f32_e32 v175, v175, v215
	v_add_f32_e32 v202, v202, v216
	ds_read_b128 v[116:119], v189 offset:8192
	s_waitcnt lgkmcnt(4)
	v_mfma_f32_32x32x16_bf16 v[32:47], v[234:237], v[160:163], v[32:47]
	v_add_f32_e32 v225, v225, v217
	v_add_f32_e32 v166, v166, v218
	v_add_f32_e32 v175, v175, v219
	v_add_f32_e32 v202, v202, v220
	ds_read_b128 v[120:123], v191 offset:8192
	s_waitcnt lgkmcnt(3)
	v_mfma_f32_32x32x16_bf16 v[16:31], v[238:241], v[160:163], v[16:31]
	v_add_f32_e32 v225, v225, v221
	v_add_f32_e32 v166, v166, v222
	v_add_f32_e32 v175, v175, v223
	v_add_f32_e32 v202, v202, v224
	ds_read_b128 v[124:127], v192 offset:8192
	s_waitcnt lgkmcnt(3)
	v_mfma_f32_32x32x16_bf16 v[80:95], v[112:115], v[140:143], v[0:15]
	v_exp_f32_e32 v209, v96
	v_exp_f32_e32 v210, v97
	ds_read_b64_tr_b16 v[242:243], v198
	ds_read_b64_tr_b16 v[244:245], v198 offset:2048
	s_waitcnt lgkmcnt(4)
	v_mfma_f32_32x32x16_bf16 v[80:95], v[116:119], v[144:147], v[80:95]
	v_exp_f32_e32 v211, v98
	v_exp_f32_e32 v212, v99
	v_cvt_pk_bf16_f32 v148, v209, v210
	ds_read_b64_tr_b16 v[246:247], v199
	ds_read_b64_tr_b16 v[248:249], v199 offset:2048
	s_waitcnt lgkmcnt(5)
	v_mfma_f32_32x32x16_bf16 v[80:95], v[120:123], v[136:139], v[80:95]
	v_exp_f32_e32 v213, v100
	v_exp_f32_e32 v214, v101
	v_cvt_pk_bf16_f32 v149, v211, v212
	ds_read_b64_tr_b16 v[226:227], v201
	ds_read_b64_tr_b16 v[228:229], v201 offset:2048
	s_waitcnt lgkmcnt(6)
	v_mfma_f32_32x32x16_bf16 v[80:95], v[124:127], v[132:135], v[80:95]
	v_exp_f32_e32 v215, v102
	v_exp_f32_e32 v216, v103
	v_cvt_pk_bf16_f32 v150, v213, v214
	v_cvt_pk_bf16_f32 v151, v215, v216
	ds_read_b64_tr_b16 v[230:231], v203
	ds_read_b64_tr_b16 v[232:233], v203 offset:2048
	s_waitcnt lgkmcnt(6)
	v_mfma_f32_32x32x16_bf16 v[64:79], v[242:245], v[148:151], v[64:79]
	v_exp_f32_e32 v217, v104
	v_exp_f32_e32 v218, v105
	ds_read_b64_tr_b16 v[234:235], v198 offset:4096
	ds_read_b64_tr_b16 v[236:237], v198 offset:6144
	s_waitcnt lgkmcnt(6)
	v_mfma_f32_32x32x16_bf16 v[48:63], v[246:249], v[148:151], v[48:63]
	v_exp_f32_e32 v219, v106
	v_exp_f32_e32 v220, v107
	v_cvt_pk_bf16_f32 v152, v217, v218
	ds_read_b64_tr_b16 v[238:239], v199 offset:4096
	ds_read_b64_tr_b16 v[240:241], v199 offset:6144
	s_waitcnt lgkmcnt(6)
	v_mfma_f32_32x32x16_bf16 v[32:47], v[226:229], v[148:151], v[32:47]
	v_exp_f32_e32 v221, v108
	v_exp_f32_e32 v222, v109
	v_cvt_pk_bf16_f32 v153, v219, v220
	ds_read_b64_tr_b16 v[242:243], v201 offset:4096
	ds_read_b64_tr_b16 v[244:245], v201 offset:6144
	s_waitcnt lgkmcnt(6)
	v_mfma_f32_32x32x16_bf16 v[16:31], v[230:233], v[148:151], v[16:31]
	v_exp_f32_e32 v223, v110
	v_exp_f32_e32 v224, v111
	v_cvt_pk_bf16_f32 v154, v221, v222
	v_cvt_pk_bf16_f32 v155, v223, v224
	ds_read_b64_tr_b16 v[246:247], v203 offset:4096
	ds_read_b64_tr_b16 v[248:249], v203 offset:6144
	s_waitcnt lgkmcnt(6)
	v_mfma_f32_32x32x16_bf16 v[64:79], v[234:237], v[152:155], v[64:79]
	s_waitcnt vmcnt(0)
	s_barrier
	s_and_b32 s1, s35, 3
	s_add_i32 s35, s35, 1
	s_cmp_lg_u32 s1, 0
	s_cbranch_scc1 .Latt_bs_2p
	v_lshlrev_b32_e32 v204, 16, v194
	v_and_b32_e32 v205, 0xffff0000, v194
	v_fma_f32 v182, v174, v182, v204
	v_fma_f32 v183, v174, v183, v205
	s_lshr_b32 s1, s35, 2
	s_add_i32 s1, s1, 1
	s_cmpk_lt_u32 s1, 0x84
	s_cbranch_scc0 .Latt_bs_2p
	s_lshl_b32 s2, s1, 14
	s_mov_b32 s3, 0
	s_lshl_b32 s4, s1, 8
	s_mov_b32 s5, 0
	v_lshl_add_u64 v[204:205], v[168:169], 0, s[2:3]
	v_lshl_add_u64 v[196:197], v[170:171], 0, s[4:5]
	v_cvt_pk_bf16_f32 v206, v182, v183
	global_load_dword v194, v[204:205], off
	global_load_dword v174, v[196:197], off
	global_store_dword v[204:205], v206, off
.Latt_bs_2p:
	v_add_f32_e32 v225, v225, v209
	v_add_f32_e32 v166, v166, v210
	v_add_f32_e32 v175, v175, v211
	v_add_f32_e32 v202, v202, v212
	ds_read_b128 v[112:115], v180 offset:32768
	s_waitcnt lgkmcnt(5)
	v_mfma_f32_32x32x16_bf16 v[48:63], v[238:241], v[152:155], v[48:63]
	v_add_f32_e32 v225, v225, v213
	v_add_f32_e32 v166, v166, v214
	v_add_f32_e32 v175, v175, v215
	v_add_f32_e32 v202, v202, v216
	ds_read_b128 v[116:119], v189 offset:32768
	s_waitcnt lgkmcnt(4)
	v_mfma_f32_32x32x16_bf16 v[32:47], v[242:245], v[152:155], v[32:47]
	v_add_f32_e32 v225, v225, v217
	v_add_f32_e32 v166, v166, v218
	v_add_f32_e32 v175, v175, v219
	v_add_f32_e32 v202, v202, v220
	ds_read_b128 v[120:123], v191 offset:32768
	s_waitcnt lgkmcnt(3)
	v_mfma_f32_32x32x16_bf16 v[16:31], v[246:249], v[152:155], v[16:31]
	v_add_f32_e32 v225, v225, v221
	v_add_f32_e32 v166, v166, v222
	v_add_f32_e32 v175, v175, v223
	v_add_f32_e32 v202, v202, v224
	ds_read_b128 v[124:127], v192 offset:32768
	s_add_i32 s16, s16, 1
	s_waitcnt lgkmcnt(3)
	v_mfma_f32_32x32x16_bf16 v[96:111], v[112:115], v[140:143], v[0:15]
	v_exp_f32_e32 v209, v80
	v_exp_f32_e32 v210, v81
	ds_read_b64_tr_b16 v[226:227], v198 offset:8192
	ds_read_b64_tr_b16 v[228:229], v198 offset:10240
	s_waitcnt lgkmcnt(4)
	v_mfma_f32_32x32x16_bf16 v[96:111], v[116:119], v[144:147], v[96:111]
	v_exp_f32_e32 v211, v82
	v_exp_f32_e32 v212, v83
	v_cvt_pk_bf16_f32 v156, v209, v210
	ds_read_b64_tr_b16 v[230:231], v199 offset:8192
	ds_read_b64_tr_b16 v[232:233], v199 offset:10240
	s_waitcnt lgkmcnt(5)
	v_mfma_f32_32x32x16_bf16 v[96:111], v[120:123], v[136:139], v[96:111]
	v_exp_f32_e32 v213, v84
	v_exp_f32_e32 v214, v85
	v_cvt_pk_bf16_f32 v157, v211, v212
	ds_read_b64_tr_b16 v[234:235], v201 offset:8192
	ds_read_b64_tr_b16 v[236:237], v201 offset:10240
	s_waitcnt lgkmcnt(6)
	v_mfma_f32_32x32x16_bf16 v[96:111], v[124:127], v[132:135], v[96:111]
	v_exp_f32_e32 v215, v86
	v_exp_f32_e32 v216, v87
	v_cvt_pk_bf16_f32 v158, v213, v214
	v_cvt_pk_bf16_f32 v159, v215, v216
	ds_read_b64_tr_b16 v[238:239], v203 offset:8192
	ds_read_b64_tr_b16 v[240:241], v203 offset:10240
	s_waitcnt lgkmcnt(6)
	v_mfma_f32_32x32x16_bf16 v[64:79], v[226:229], v[156:159], v[64:79]
	v_exp_f32_e32 v217, v88
	v_exp_f32_e32 v218, v89
	ds_read_b64_tr_b16 v[242:243], v198 offset:12288
	ds_read_b64_tr_b16 v[244:245], v198 offset:14336
	s_waitcnt lgkmcnt(6)
	v_mfma_f32_32x32x16_bf16 v[48:63], v[230:233], v[156:159], v[48:63]
	v_exp_f32_e32 v219, v90
	v_exp_f32_e32 v220, v91
	v_cvt_pk_bf16_f32 v160, v217, v218
	ds_read_b64_tr_b16 v[246:247], v199 offset:12288
	ds_read_b64_tr_b16 v[248:249], v199 offset:14336
	s_waitcnt lgkmcnt(6)
	v_mfma_f32_32x32x16_bf16 v[32:47], v[234:237], v[156:159], v[32:47]
	v_exp_f32_e32 v221, v92
	v_exp_f32_e32 v222, v93
	v_cvt_pk_bf16_f32 v161, v219, v220
	ds_read_b64_tr_b16 v[226:227], v201 offset:12288
	ds_read_b64_tr_b16 v[228:229], v201 offset:14336
	s_waitcnt lgkmcnt(6)
	v_mfma_f32_32x32x16_bf16 v[16:31], v[238:241], v[156:159], v[16:31]
	v_exp_f32_e32 v223, v94
	v_exp_f32_e32 v224, v95
	v_cvt_pk_bf16_f32 v162, v221, v222
	v_cvt_pk_bf16_f32 v163, v223, v224
	ds_read_b64_tr_b16 v[230:231], v203 offset:12288
	ds_read_b64_tr_b16 v[232:233], v203 offset:14336
	s_waitcnt lgkmcnt(6)
	v_mfma_f32_32x32x16_bf16 v[64:79], v[242:245], v[160:163], v[64:79]
	v_add_f32_e32 v225, v225, v209
	v_add_f32_e32 v166, v166, v210
	v_add_f32_e32 v175, v175, v211
	v_add_f32_e32 v202, v202, v212
	ds_read_b128 v[112:115], v180 offset:40960
	s_waitcnt lgkmcnt(5)
	v_mfma_f32_32x32x16_bf16 v[48:63], v[246:249], v[160:163], v[48:63]
	v_add_f32_e32 v225, v225, v213
	v_add_f32_e32 v166, v166, v214
	v_add_f32_e32 v175, v175, v215
	v_add_f32_e32 v202, v202, v216
	ds_read_b128 v[116:119], v189 offset:40960
	s_waitcnt lgkmcnt(4)
	v_mfma_f32_32x32x16_bf16 v[32:47], v[226:229], v[160:163], v[32:47]
	v_add_f32_e32 v225, v225, v217
	v_add_f32_e32 v166, v166, v218
	v_add_f32_e32 v175, v175, v219
	v_add_f32_e32 v202, v202, v220
	ds_read_b128 v[120:123], v191 offset:40960
	s_waitcnt lgkmcnt(3)
	v_mfma_f32_32x32x16_bf16 v[16:31], v[230:233], v[160:163], v[16:31]
	v_add_f32_e32 v225, v225, v221
	v_add_f32_e32 v166, v166, v222
	v_add_f32_e32 v175, v175, v223
	v_add_f32_e32 v202, v202, v224
	ds_read_b128 v[124:127], v192 offset:40960
	s_waitcnt lgkmcnt(3)
	v_mfma_f32_32x32x16_bf16 v[80:95], v[112:115], v[140:143], v[0:15]
	v_exp_f32_e32 v209, v96
	v_exp_f32_e32 v210, v97
	ds_read_b64_tr_b16 v[234:235], v198 offset:32768
	ds_read_b64_tr_b16 v[236:237], v198 offset:34816
	s_waitcnt lgkmcnt(4)
	v_mfma_f32_32x32x16_bf16 v[80:95], v[116:119], v[144:147], v[80:95]
	v_exp_f32_e32 v211, v98
	v_exp_f32_e32 v212, v99
	v_cvt_pk_bf16_f32 v148, v209, v210
	ds_read_b64_tr_b16 v[238:239], v199 offset:32768
	ds_read_b64_tr_b16 v[240:241], v199 offset:34816
	s_waitcnt lgkmcnt(5)
	v_mfma_f32_32x32x16_bf16 v[80:95], v[120:123], v[136:139], v[80:95]
	v_exp_f32_e32 v213, v100
	v_exp_f32_e32 v214, v101
	v_cvt_pk_bf16_f32 v149, v211, v212
	ds_read_b64_tr_b16 v[242:243], v201 offset:32768
	ds_read_b64_tr_b16 v[244:245], v201 offset:34816
	s_waitcnt lgkmcnt(6)
	v_mfma_f32_32x32x16_bf16 v[80:95], v[124:127], v[132:135], v[80:95]
	v_exp_f32_e32 v215, v102
	v_exp_f32_e32 v216, v103
	v_cvt_pk_bf16_f32 v150, v213, v214
	v_cvt_pk_bf16_f32 v151, v215, v216
	ds_read_b64_tr_b16 v[246:247], v203 offset:32768
	ds_read_b64_tr_b16 v[248:249], v203 offset:34816
	s_waitcnt lgkmcnt(6)
	v_mfma_f32_32x32x16_bf16 v[64:79], v[234:237], v[148:151], v[64:79]
	v_exp_f32_e32 v217, v104
	v_exp_f32_e32 v218, v105
	ds_read_b64_tr_b16 v[226:227], v198 offset:36864
	ds_read_b64_tr_b16 v[228:229], v198 offset:38912
	s_waitcnt lgkmcnt(6)
	v_mfma_f32_32x32x16_bf16 v[48:63], v[238:241], v[148:151], v[48:63]
	v_exp_f32_e32 v219, v106
	v_exp_f32_e32 v220, v107
	v_cvt_pk_bf16_f32 v152, v217, v218
	ds_read_b64_tr_b16 v[230:231], v199 offset:36864
	ds_read_b64_tr_b16 v[232:233], v199 offset:38912
	s_waitcnt lgkmcnt(6)
	v_mfma_f32_32x32x16_bf16 v[32:47], v[242:245], v[148:151], v[32:47]
	v_exp_f32_e32 v221, v108
	v_exp_f32_e32 v222, v109
	v_cvt_pk_bf16_f32 v153, v219, v220
	ds_read_b64_tr_b16 v[234:235], v201 offset:36864
	ds_read_b64_tr_b16 v[236:237], v201 offset:38912
	s_waitcnt lgkmcnt(6)
	v_mfma_f32_32x32x16_bf16 v[16:31], v[246:249], v[148:151], v[16:31]
	v_exp_f32_e32 v223, v110
	v_exp_f32_e32 v224, v111
	v_cvt_pk_bf16_f32 v154, v221, v222
	v_cvt_pk_bf16_f32 v155, v223, v224
	ds_read_b64_tr_b16 v[238:239], v203 offset:36864
	ds_read_b64_tr_b16 v[240:241], v203 offset:38912
	s_waitcnt lgkmcnt(6)
	v_mfma_f32_32x32x16_bf16 v[64:79], v[226:229], v[152:155], v[64:79]
	s_waitcnt vmcnt(0)
	s_barrier
	s_and_b32 s1, s35, 3
	s_add_i32 s35, s35, 1
	s_cmp_lg_u32 s1, 0
	s_cbranch_scc1 .Latt_bs_3p
	v_lshlrev_b32_e32 v204, 16, v194
	v_and_b32_e32 v205, 0xffff0000, v194
	v_fma_f32 v182, v174, v182, v204
	v_fma_f32 v183, v174, v183, v205
	s_lshr_b32 s1, s35, 2
	s_add_i32 s1, s1, 1
	s_cmpk_lt_u32 s1, 0x84
	s_cbranch_scc0 .Latt_bs_3p
	s_lshl_b32 s2, s1, 14
	s_mov_b32 s3, 0
	s_lshl_b32 s4, s1, 8
	s_mov_b32 s5, 0
	v_lshl_add_u64 v[204:205], v[168:169], 0, s[2:3]
	v_lshl_add_u64 v[196:197], v[170:171], 0, s[4:5]
	v_cvt_pk_bf16_f32 v206, v182, v183
	global_load_dword v194, v[204:205], off
	global_load_dword v174, v[196:197], off
	global_store_dword v[204:205], v206, off
.Latt_bs_3p:
	v_add_f32_e32 v225, v225, v209
	v_add_f32_e32 v166, v166, v210
	v_add_f32_e32 v175, v175, v211
	v_add_f32_e32 v202, v202, v212
	ds_read_b128 v[112:115], v178
	s_waitcnt lgkmcnt(5)
	v_mfma_f32_32x32x16_bf16 v[48:63], v[230:233], v[152:155], v[48:63]
	v_add_f32_e32 v225, v225, v213
	v_add_f32_e32 v166, v166, v214
	v_add_f32_e32 v175, v175, v215
	v_add_f32_e32 v202, v202, v216
	ds_read_b128 v[116:119], v128
	s_waitcnt lgkmcnt(4)
	v_mfma_f32_32x32x16_bf16 v[32:47], v[234:237], v[152:155], v[32:47]
	v_add_f32_e32 v225, v225, v217
	v_add_f32_e32 v166, v166, v218
	v_add_f32_e32 v175, v175, v219
	v_add_f32_e32 v202, v202, v220
	ds_read_b128 v[120:123], v130
	s_waitcnt lgkmcnt(3)
	v_mfma_f32_32x32x16_bf16 v[16:31], v[238:241], v[152:155], v[16:31]
	v_add_f32_e32 v225, v225, v221
	v_add_f32_e32 v166, v166, v222
	v_add_f32_e32 v175, v175, v223
	v_add_f32_e32 v202, v202, v224
	ds_read_b128 v[124:127], v131
	s_add_i32 s16, s16, 1
	ds_read_b64_tr_b16 v[226:227], v198 offset:40960
	ds_read_b64_tr_b16 v[228:229], v198 offset:43008
	ds_read_b64_tr_b16 v[230:231], v199 offset:40960
	ds_read_b64_tr_b16 v[232:233], v199 offset:43008
	ds_read_b64_tr_b16 v[234:235], v201 offset:40960
	ds_read_b64_tr_b16 v[236:237], v201 offset:43008
	ds_read_b64_tr_b16 v[238:239], v203 offset:40960
	ds_read_b64_tr_b16 v[240:241], v203 offset:43008
	ds_read_b64_tr_b16 v[242:243], v198 offset:45056
	ds_read_b64_tr_b16 v[244:245], v198 offset:47104
	ds_read_b64_tr_b16 v[246:247], v199 offset:45056
	ds_read_b64_tr_b16 v[248:249], v199 offset:47104
	ds_read_b64_tr_b16 v[112:113], v201 offset:45056
	ds_read_b64_tr_b16 v[114:115], v201 offset:47104
	ds_read_b64_tr_b16 v[120:121], v203 offset:45056
	ds_read_b64_tr_b16 v[122:123], v203 offset:47104
	v_exp_f32_e32 v209, v80
	v_exp_f32_e32 v210, v81
	v_exp_f32_e32 v211, v82
	v_exp_f32_e32 v212, v83
	v_exp_f32_e32 v213, v84
	v_exp_f32_e32 v214, v85
	v_exp_f32_e32 v215, v86
	v_exp_f32_e32 v216, v87
	v_exp_f32_e32 v217, v88
	v_exp_f32_e32 v218, v89
	v_exp_f32_e32 v219, v90
	v_exp_f32_e32 v220, v91
	v_exp_f32_e32 v221, v92
	v_exp_f32_e32 v222, v93
	v_exp_f32_e32 v223, v94
	v_exp_f32_e32 v224, v95
	s_nop 0
	v_cvt_pk_bf16_f32 v156, v209, v210
	v_cvt_pk_bf16_f32 v157, v211, v212
	v_cvt_pk_bf16_f32 v158, v213, v214
	v_cvt_pk_bf16_f32 v159, v215, v216
	v_cvt_pk_bf16_f32 v160, v217, v218
	v_cvt_pk_bf16_f32 v161, v219, v220
	v_cvt_pk_bf16_f32 v162, v221, v222
	v_cvt_pk_bf16_f32 v163, v223, v224
	v_add_f32_e32 v225, v225, v209
	v_add_f32_e32 v166, v166, v210
	v_add_f32_e32 v175, v175, v211
	v_add_f32_e32 v202, v202, v212
	v_add_f32_e32 v225, v225, v213
	v_add_f32_e32 v166, v166, v214
	v_add_f32_e32 v175, v175, v215
	v_add_f32_e32 v202, v202, v216
	v_add_f32_e32 v225, v225, v217
	v_add_f32_e32 v166, v166, v218
	v_add_f32_e32 v175, v175, v219
	v_add_f32_e32 v202, v202, v220
	v_add_f32_e32 v225, v225, v221
	v_add_f32_e32 v166, v166, v222
	v_add_f32_e32 v175, v175, v223
	v_add_f32_e32 v202, v202, v224
	s_waitcnt lgkmcnt(0)
	v_mfma_f32_32x32x16_bf16 v[64:79], v[226:229], v[156:159], v[64:79]
	v_mfma_f32_32x32x16_bf16 v[48:63], v[230:233], v[156:159], v[48:63]
	v_mfma_f32_32x32x16_bf16 v[32:47], v[234:237], v[156:159], v[32:47]
	v_mfma_f32_32x32x16_bf16 v[16:31], v[238:241], v[156:159], v[16:31]
	v_mfma_f32_32x32x16_bf16 v[64:79], v[242:245], v[160:163], v[64:79]
	v_mfma_f32_32x32x16_bf16 v[48:63], v[246:249], v[160:163], v[48:63]
	v_mfma_f32_32x32x16_bf16 v[32:47], v[112:115], v[160:163], v[32:47]
	v_mfma_f32_32x32x16_bf16 v[16:31], v[120:123], v[160:163], v[16:31]
	v_add_f32_e32 v225, v225, v166
	v_add_f32_e32 v175, v175, v202
	v_add_f32_e32 v80, v225, v175
	v_and_b32_e32 v196, 63, v188
	s_cmpk_lt_u32 s34, 0x100
	s_cselect_b64 s[4:5], -1, 0
	s_lshl_b32 s0, s31, 14
	s_waitcnt vmcnt(0)
	s_barrier
	ds_bpermute_b32 v81, v195, v80
	s_nop 7
	s_nop 7
	s_cmp_eq_u32 s30, 1
	s_waitcnt lgkmcnt(0)
	v_add_f32_e32 v80, v80, v81
	v_cndmask_b32_e64 v81, v164, 1.0, s[4:5]
	v_div_scale_f32 v82, s[16:17], v80, v80, v81
	v_rcp_f32_e32 v83, v82
	s_nop 0
	v_fma_f32 v84, -v82, v83, 1.0
	v_fmac_f32_e32 v83, v84, v83
	v_div_scale_f32 v84, vcc, v81, v80, v81
	v_mul_f32_e32 v85, v84, v83
	v_fma_f32 v86, -v82, v85, v84
	v_fmac_f32_e32 v85, v86, v83
	v_fma_f32 v82, -v82, v85, v84
	v_div_fmas_f32 v82, v82, v83, v85
	v_div_fixup_f32 v92, v82, v80, v81
	v_pk_mul_f32 v[88:89], v[64:65], v[92:93] op_sel_hi:[1,0]
	v_pk_mul_f32 v[90:91], v[66:67], v[92:93] op_sel_hi:[1,0]
	v_pk_mul_f32 v[82:83], v[68:69], v[92:93] op_sel_hi:[1,0]
	v_pk_mul_f32 v[86:87], v[70:71], v[92:93] op_sel_hi:[1,0]
	v_pk_mul_f32 v[80:81], v[72:73], v[92:93] op_sel_hi:[1,0]
	v_pk_mul_f32 v[84:85], v[74:75], v[92:93] op_sel_hi:[1,0]
	v_pk_mul_f32 v[72:73], v[76:77], v[92:93] op_sel_hi:[1,0]
	v_pk_mul_f32 v[78:79], v[78:79], v[92:93] op_sel_hi:[1,0]
	v_pk_mul_f32 v[68:69], v[48:49], v[92:93] op_sel_hi:[1,0]
	v_pk_mul_f32 v[76:77], v[50:51], v[92:93] op_sel_hi:[1,0]
	v_pk_mul_f32 v[66:67], v[52:53], v[92:93] op_sel_hi:[1,0]
	v_pk_mul_f32 v[74:75], v[54:55], v[92:93] op_sel_hi:[1,0]
	v_pk_mul_f32 v[64:65], v[56:57], v[92:93] op_sel_hi:[1,0]
	v_pk_mul_f32 v[70:71], v[58:59], v[92:93] op_sel_hi:[1,0]
	v_pk_mul_f32 v[54:55], v[60:61], v[92:93] op_sel_hi:[1,0]
	v_pk_mul_f32 v[60:61], v[62:63], v[92:93] op_sel_hi:[1,0]
	v_pk_mul_f32 v[50:51], v[32:33], v[92:93] op_sel_hi:[1,0]
	v_pk_mul_f32 v[58:59], v[34:35], v[92:93] op_sel_hi:[1,0]
	v_pk_mul_f32 v[48:49], v[36:37], v[92:93] op_sel_hi:[1,0]
	v_pk_mul_f32 v[56:57], v[38:39], v[92:93] op_sel_hi:[1,0]
	v_pk_mul_f32 v[40:41], v[40:41], v[92:93] op_sel_hi:[1,0]
	v_pk_mul_f32 v[52:53], v[42:43], v[92:93] op_sel_hi:[1,0]
	v_pk_mul_f32 v[36:37], v[44:45], v[92:93] op_sel_hi:[1,0]
	v_pk_mul_f32 v[44:45], v[46:47], v[92:93] op_sel_hi:[1,0]
	v_pk_mul_f32 v[34:35], v[16:17], v[92:93] op_sel_hi:[1,0]
	v_pk_mul_f32 v[42:43], v[18:19], v[92:93] op_sel_hi:[1,0]
	v_pk_mul_f32 v[32:33], v[20:21], v[92:93] op_sel_hi:[1,0]
	v_pk_mul_f32 v[38:39], v[22:23], v[92:93] op_sel_hi:[1,0]
	v_pk_mul_f32 v[20:21], v[24:25], v[92:93] op_sel_hi:[1,0]
	v_pk_mul_f32 v[22:23], v[26:27], v[92:93] op_sel_hi:[1,0]
	v_pk_mul_f32 v[16:17], v[28:29], v[92:93] op_sel_hi:[1,0]
	v_pk_mul_f32 v[18:19], v[30:31], v[92:93] op_sel_hi:[1,0]
	v_lshl_add_u32 v24, v196, 2, s0
	s_cbranch_scc0 .LBB0_446
	ds_write2st64_b32 v24, v88, v89 offset1:1
	ds_write2st64_b32 v24, v90, v91 offset0:2 offset1:3
	ds_write2st64_b32 v24, v82, v83 offset0:4 offset1:5
	ds_write2st64_b32 v24, v86, v87 offset0:6 offset1:7
	ds_write2st64_b32 v24, v80, v81 offset0:8 offset1:9
	ds_write2st64_b32 v24, v84, v85 offset0:10 offset1:11
	ds_write2st64_b32 v24, v72, v73 offset0:12 offset1:13
	ds_write2st64_b32 v24, v78, v79 offset0:14 offset1:15
	ds_write2st64_b32 v24, v68, v69 offset0:16 offset1:17
	ds_write2st64_b32 v24, v76, v77 offset0:18 offset1:19
	ds_write2st64_b32 v24, v66, v67 offset0:20 offset1:21
	ds_write2st64_b32 v24, v74, v75 offset0:22 offset1:23
	ds_write2st64_b32 v24, v64, v65 offset0:24 offset1:25
	ds_write2st64_b32 v24, v70, v71 offset0:26 offset1:27
	ds_write2st64_b32 v24, v54, v55 offset0:28 offset1:29
	ds_write2st64_b32 v24, v60, v61 offset0:30 offset1:31
	ds_write2st64_b32 v24, v50, v51 offset0:32 offset1:33
	ds_write2st64_b32 v24, v58, v59 offset0:34 offset1:35
	ds_write2st64_b32 v24, v48, v49 offset0:36 offset1:37
	ds_write2st64_b32 v24, v56, v57 offset0:38 offset1:39
	ds_write2st64_b32 v24, v40, v41 offset0:40 offset1:41
	ds_write2st64_b32 v24, v52, v53 offset0:42 offset1:43
	ds_write2st64_b32 v24, v36, v37 offset0:44 offset1:45
	ds_write2st64_b32 v24, v44, v45 offset0:46 offset1:47
	ds_write2st64_b32 v24, v34, v35 offset0:48 offset1:49
	ds_write2st64_b32 v24, v42, v43 offset0:50 offset1:51
	ds_write2st64_b32 v24, v32, v33 offset0:52 offset1:53
	ds_write2st64_b32 v24, v38, v39 offset0:54 offset1:55
	ds_write2st64_b32 v24, v20, v21 offset0:56 offset1:57
	ds_write2st64_b32 v24, v22, v23 offset0:58 offset1:59
	ds_write2st64_b32 v24, v16, v17 offset0:60 offset1:61
	ds_write2st64_b32 v24, v18, v19 offset0:62 offset1:63
